# nt also on the norm phases' row/slab loads; cumulative: scan, conversion+w_ada, prep Z, norm1/norm2
# speedup vs baseline: 1.0196x; 1.0011x over previous
; #define LAS __attribute__((address_space(3)))
; __device__ __forceinline__ void norm_mod_phase(const Frame& F0, const Args& a0, int l, int which, bool skip_ctx, const float* slabgate) {
;     const Frame F = relaunder(F0); const Args a = relaunder_args(a0);
;     const float* X = (const float*)(a.ws + WS_X); bf16* H = (bf16*)(a.ws + WS_H);
;     const float* gain = a.in[which ? I_NFFN : I_NMIX] + (size_t)l * DM;
;     const float* modl = (const float*)(a.ws + WS_MOD) + (size_t)l * 5 * D6;
;     const int gw = F.vcu * NWAVES + F.wave, NGW = F.G * NWAVES;
;     LAS f32x4* ca = (LAS f32x4*)(F.lds + RING_OFF); LAS f32x4* cb = ca + 5 * (DM / 4); LAS f32x4* cg = cb + 5 * (DM / 4);
;     { f32x4 g[5], sc[5], sh[5];
; #pragma unroll
;       for (int r = 0; r < 5; ++r) { const float* shift = modl + (size_t)r * D6 + (which ? 3 * DM : 0);
;           g[r] = ((const f32x4*)gain)[F.tid]; sc[r] = ((const f32x4*)(shift + DM))[F.tid]; sh[r] = ((const f32x4*)shift)[F.tid]; }
;       f32x4 gt4 = (f32x4){0.f, 0.f, 0.f, 0.f}; if (slabgate != nullptr) gt4 = ((const f32x4*)slabgate)[F.tid];
;       __builtin_amdgcn_sched_barrier(0);
; #pragma unroll
;       for (int r = 0; r < 5; ++r) { ca[r * (DM / 4) + F.tid] = g[r] * (sc[r] + 1.0f); cb[r * (DM / 4) + F.tid] = sh[r]; }
;       cg[F.tid] = gt4; }
; __global__ void __launch_bounds__(NTHREADS, 2) fwd(Args args) {
;     ...
;     for (int l = 0; l < DEPTH; ++l) {
;         const bool last = (l == DEPTH - 1);
;         const float* modl = (const float*)(ws + WS_MOD) + (size_t)l * 5 * D6;
;         const float* zmod = (const float*)(ws + WS_ZERO);
;         if (IN(GP(l, 0))) for (int rep = 0; rep < REP_NORM; ++rep) { norm_mod_phase(F, args, l, 0, false, (l > 0 && rep == 0) ? modl - 5 * D6 + 3 * D6 + 5 * DM : nullptr); if (REP_NB && rep + 1 < REP_NORM) xcd_barrier(bar); }
.LBB0_165:
	s_mul_i32 s2, s24, 0x3c000
	v_readlane_b32 s0, v221, 48
	s_mul_hi_u32 s1, s24, 0x3c000
	v_writelane_b32 v220, s2, 21
	s_add_u32 s2, s0, s2
	v_readlane_b32 s0, v221, 49
	v_writelane_b32 v220, s1, 22
	s_addc_u32 s3, s0, s1
	v_writelane_b32 v220, s2, 23
	s_mul_i32 s75, s24, 9
	s_mov_b32 s25, s85
	v_writelane_b32 v220, s3, 24
	s_add_i32 s2, s75, 1
	s_cmp_le_i32 s64, s2
	s_cselect_b64 s[0:1], -1, 0
	s_cmp_lt_i32 s2, s65
	s_cselect_b64 s[2:3], -1, 0
	s_and_b64 s[0:1], s[0:1], s[2:3]
	s_andn2_b64 vcc, exec, s[0:1]
	v_writelane_b32 v220, s75, 25
	s_cbranch_vccnz .LBB0_196
	s_mov_b32 s2, s92
	s_mov_b32 s10, s93
	s_mov_b32 s6, s94
	s_mov_b32 s3, s95
	v_readlane_b32 s48, v221, 0
	v_mbcnt_lo_u32_b32 v64, -1, 0
	v_mbcnt_hi_u32_b32 v64, -1, v64
	v_readlane_b32 s49, v221, 1
	v_readlane_b32 s50, v221, 2
	v_readlane_b32 s51, v221, 3
	s_mov_b64 s[6:7], s[48:49]
	s_mov_b64 s[8:9], s[50:51]
	v_readlane_b32 s52, v221, 4
	v_readlane_b32 s53, v221, 5
	v_readlane_b32 s54, v221, 6
	v_readlane_b32 s55, v221, 7
	s_mov_b64 s[8:9], s[52:53]
	s_mov_b64 s[12:13], s[54:55]
	v_readlane_b32 s56, v221, 8
	v_readlane_b32 s57, v221, 9
	s_mov_b64 s[12:13], s[56:57]
	v_readlane_b32 s58, v221, 10
	v_readlane_b32 s59, v221, 11
	s_mov_b64 s[12:13], s[58:59]
	v_readlane_b32 s60, v221, 12
	v_readlane_b32 s61, v221, 13
	v_readlane_b32 s62, v221, 14
	v_readlane_b32 s63, v221, 15
	s_mov_b64 s[18:19], s[60:61]
	s_mov_b64 s[12:13], s[62:63]
	v_readlane_b32 s64, v221, 16
	v_readlane_b32 s65, v221, 17
	s_mov_b64 s[12:13], s[64:65]
	v_readlane_b32 s66, v221, 18
	v_readlane_b32 s67, v221, 19
	s_mov_b64 s[12:13], s[66:67]
	v_readlane_b32 s68, v221, 20
	v_readlane_b32 s69, v221, 21
	s_mov_b64 s[12:13], s[68:69]
	v_readlane_b32 s70, v221, 22
	v_readlane_b32 s71, v221, 23
	s_mov_b64 s[12:13], s[70:71]
	v_readlane_b32 s72, v221, 24
	v_readlane_b32 s73, v221, 25
	s_mov_b64 s[12:13], s[72:73]
	v_readlane_b32 s74, v221, 26
	v_readlane_b32 s75, v221, 27
	s_mov_b64 s[12:13], s[74:75]
	v_readlane_b32 s76, v221, 28
	v_readlane_b32 s77, v221, 29
	s_mov_b64 s[12:13], s[76:77]
	v_readlane_b32 s78, v221, 30
	v_readlane_b32 s79, v221, 31
	s_mov_b64 s[12:13], s[78:79]
	s_mov_b64 s[12:13], s[40:41]
	s_cmp_lg_u32 s24, 0
	s_mov_b64 s[12:13], s[42:43]
	s_cselect_b64 s[4:5], -1, 0
	s_cmp_eq_u32 s24, 0
	s_cselect_b64 s[14:15], -1, 0
	s_lshl_b64 s[16:17], s[24:25], 13
	s_mov_b64 s[12:13], s[44:45]
	s_add_u32 s16, s18, s16
	s_waitcnt vmcnt(0)
	v_lshl_add_u32 v48, s3, 6, v64
	s_mov_b64 s[12:13], s[46:47]
	s_addc_u32 s17, s19, s17
	v_readlane_b32 s11, v220, 21
	s_add_u32 s18, s12, s11
	v_readlane_b32 s11, v220, 22
	v_ashrrev_i32_e32 v49, 31, v48
	s_addc_u32 s19, s13, s11
	v_lshlrev_b64 v[4:5], 4, v[48:49]
	v_lshl_add_u64 v[32:33], s[18:19], 0, v[4:5]
	s_mov_b32 s11, 0x102000
	v_lshl_add_u64 v[0:1], s[16:17], 0, v[4:5]
	v_add_co_u32_e32 v4, vcc, s11, v32
	s_mov_b32 s73, 0x100000
	s_nop 0
	v_addc_co_u32_e32 v5, vcc, 0, v33, vcc
	v_add_co_u32_e32 v6, vcc, s73, v32
	s_mov_b32 s11, 0x10e000
	s_nop 0
	v_addc_co_u32_e32 v7, vcc, 0, v33, vcc
	v_add_co_u32_e32 v8, vcc, s11, v32
	s_mov_b32 s11, 0x10c000
	s_nop 0
	v_addc_co_u32_e32 v9, vcc, 0, v33, vcc
	v_add_co_u32_e32 v10, vcc, s11, v32
	s_mov_b32 s11, 0x11a000
	s_nop 0
	v_addc_co_u32_e32 v11, vcc, 0, v33, vcc
	v_add_co_u32_e32 v16, vcc, s11, v32
	s_mov_b32 s11, 0x118000
	s_nop 0
	v_addc_co_u32_e32 v17, vcc, 0, v33, vcc
	v_add_co_u32_e32 v18, vcc, s11, v32
	s_mov_b32 s11, 0x126000
	s_nop 0
	v_addc_co_u32_e32 v19, vcc, 0, v33, vcc
	s_waitcnt vmcnt(1)
	v_add_co_u32_e32 v24, vcc, s11, v32
	global_load_dwordx4 v[0:3], v[0:1], off nt
	s_nop 0
	v_addc_co_u32_e32 v25, vcc, 0, v33, vcc
	v_add_co_u32_e32 v26, vcc, 0x124000, v32
	global_load_dwordx4 v[20:23], v[4:5], off nt
	s_nop 0
	global_load_dwordx4 v[4:7], v[6:7], off nt
	v_addc_co_u32_e32 v27, vcc, 0, v33, vcc
	v_add_co_u32_e32 v34, vcc, 0x132000, v32
	global_load_dwordx4 v[12:15], v[8:9], off nt
	s_nop 0
	global_load_dwordx4 v[8:11], v[10:11], off nt
	v_addc_co_u32_e32 v35, vcc, 0, v33, vcc
	v_add_co_u32_e32 v32, vcc, 0x130000, v32
	global_load_dwordx4 v[28:31], v[16:17], off nt
	s_nop 0
	global_load_dwordx4 v[16:19], v[18:19], off nt
	v_addc_co_u32_e32 v33, vcc, 0, v33, vcc
	global_load_dwordx4 v[36:39], v[24:25], off nt
	s_nop 0
	global_load_dwordx4 v[24:27], v[26:27], off nt
	s_nop 0
	global_load_dwordx4 v[40:43], v[34:35], off nt
	s_nop 0
	global_load_dwordx4 v[32:35], v[32:33], off nt
	s_and_b64 vcc, exec, s[14:15]
	s_cbranch_vccnz .LBB0_168
	v_readlane_b32 s16, v220, 23
	v_readlane_b32 s17, v220, 24
	s_nop 1
	v_lshl_add_u64 v[44:45], v[48:49], 4, s[16:17]
	v_add_co_u32_e32 v44, vcc, 0xffff2000, v44
	s_nop 1
	v_addc_co_u32_e32 v45, vcc, -1, v45, vcc
	global_load_dwordx4 v[44:47], v[44:45], off nt
	s_branch .LBB0_169

; #define NM_NEXT(mm) do { while ((mm) < mlim && skip_ctx && ((mm) % TT) < CTXL) (mm) += mstep; } while (0)
; __device__ __forceinline__ void norm_mod_phase(const Frame& F0, const Args& a0, int l, int which, bool skip_ctx, const float* slabgate) {
;     ...
;     NM_NEXT(m);
;     f32x4 v[8], vn[8];
;     const bool fromin = (l == 0 && which == 0);
;     ...
;     if (m < mlim) { const f32x4* xr = NM_ROW(m);
; #pragma unroll
;         for (int j = 0; j < 8; ++j) v[j] = xr[64 * j]; }
.LBB0_180:
	s_lshl_b64 s[16:17], s[16:17], 13
	s_add_u32 s14, s14, s16
	v_ashrrev_i32_e32 v65, 31, v64
	s_addc_u32 s15, s15, s17
	v_lshlrev_b64 v[8:9], 4, v[64:65]
	v_lshl_add_u64 v[0:1], s[14:15], 0, v[8:9]
	s_movk_i32 s14, 0x1000
	global_load_dwordx4 v[60:63], v[0:1], off nt
	global_load_dwordx4 v[56:59], v[0:1], off offset:1024 nt
	global_load_dwordx4 v[52:55], v[0:1], off offset:2048 nt
	global_load_dwordx4 v[48:51], v[0:1], off offset:3072 nt
	v_add_co_u32_e32 v0, vcc, s14, v0
	v_lshl_add_u64 v[10:11], s[12:13], 0, v[8:9]
	s_nop 0
	v_addc_co_u32_e32 v1, vcc, 0, v1, vcc
	global_load_dwordx4 v[44:47], v[0:1], off nt
	global_load_dwordx4 v[40:43], v[0:1], off offset:1024 nt
	global_load_dwordx4 v[4:7], v[0:1], off offset:2048 nt
	s_nop 0
	global_load_dwordx4 v[0:3], v[0:1], off offset:3072 nt
	s_mov_b64 s[14:15], 0x50000000
	v_lshl_add_u64 v[68:69], s[10:11], 0, v[8:9]
	v_lshlrev_b32_e32 v8, 2, v64
	v_lshl_add_u64 v[66:67], v[10:11], 0, s[14:15]
	s_add_i32 s14, 0, 0x14000
	v_xor_b32_e32 v77, 4, v8
	v_xor_b32_e32 v78, 8, v8
	v_xor_b32_e32 v79, 16, v8
	v_xor_b32_e32 v80, 32, v8
	v_xor_b32_e32 v81, 64, v8
	v_xor_b32_e32 v82, 0x80, v8
	v_lshl_add_u64 v[8:9], v[64:65], 3, s[12:13]
	s_mov_b64 s[12:13], 0x1c800000
	v_lshl_add_u32 v76, v64, 4, s14
	v_lshl_add_u64 v[70:71], v[8:9], 0, s[12:13]
	s_xor_b64 s[12:13], s[4:5], -1
	s_branch .LBB0_182

; #define NM_NEXT(mm) do { while ((mm) < mlim && skip_ctx && ((mm) % TT) < CTXL) (mm) += mstep; } while (0)
; __device__ __forceinline__ void norm_mod_phase(const Frame& F0, const Args& a0, int l, int which, bool skip_ctx, const float* slabgate) {
;     ...
;     while (m < mlim) {
;         int mn = m + mstep; NM_NEXT(mn);
;         if (mn < mlim) { const f32x4* xr = NM_ROW(mn);
; #pragma unroll
;             for (int j = 0; j < 8; ++j) vn[j] = xr[64 * j]; }
;         const int b = m / TT, t = m - b * TT; const int r = (t < CTXL) ? 4 : b;
;         float ss = 0.f;
;         if (slabgate != nullptr && m >= 8192) {
;             const f32x4* sl = (const f32x4*)((const float*)(a.ws + WS_SLAB) + (size_t)(m - 8192) * DM) + F.lane;
; #pragma unroll
;             for (int jp = 0; jp < 4; ++jp) {
;                 f32x4 sv[2][8];
; #pragma unroll
;                 for (int jj = 0; jj < 2; ++jj)
; #pragma unroll
;                     for (int ks = 0; ks < 8; ++ks) sv[jj][ks] = sl[(size_t)ks * 1024 * (DM / 4) + 64 * (2 * jp + jj)];
;                 __builtin_amdgcn_sched_barrier(0);
; #pragma unroll
;                 for (int jj = 0; jj < 2; ++jj) { const int j = 2 * jp + jj;
;                     const f32x4 sum = ((sv[jj][0] + sv[jj][1]) + (sv[jj][2] + sv[jj][3])) + ((sv[jj][4] + sv[jj][5]) + (sv[jj][6] + sv[jj][7]));
;                     v[j] = v[j] + cg[F.lane + 64 * j] * sum;
;                     ((f32x4*)(a.ws + WS_X) + (size_t)m * (DM / 4) + F.lane)[64 * j] = v[j]; }
;                 __builtin_amdgcn_sched_barrier(0);
;             }
.LBB0_191:
	s_lshl_b64 s[22:23], s[68:69], 13
	s_add_u32 s4, s4, s22
	s_addc_u32 s5, s5, s23
	v_lshl_add_u64 v[24:25], v[64:65], 4, s[4:5]
	global_load_dwordx4 v[20:23], v[24:25], off nt
	global_load_dwordx4 v[16:19], v[24:25], off offset:1024 nt
	global_load_dwordx4 v[12:15], v[24:25], off offset:2048 nt
	global_load_dwordx4 v[8:11], v[24:25], off offset:3072 nt
	v_add_co_u32_e32 v24, vcc, 0x1000, v24
	s_nop 1
	v_addc_co_u32_e32 v25, vcc, 0, v25, vcc
	global_load_dwordx4 v[36:39], v[24:25], off nt
	global_load_dwordx4 v[32:35], v[24:25], off offset:1024 nt
	global_load_dwordx4 v[28:31], v[24:25], off offset:2048 nt
	s_nop 0
	global_load_dwordx4 v[24:27], v[24:25], off offset:3072 nt
.LBB0_192:
	s_cmpk_lt_i32 s30, 0x2000
	s_cselect_b64 s[4:5], -1, 0
	s_or_b64 s[4:5], s[12:13], s[4:5]
	s_and_b64 vcc, exec, s[4:5]
	s_cbranch_vccnz .LBB0_194
	s_add_i32 s84, s30, 0xffffe000
	s_lshl_b64 s[4:5], s[84:85], 13
	v_lshl_add_u64 v[74:75], v[66:67], 0, s[4:5]
	v_add_co_u32_e32 v148, vcc, 0x800000, v74
	s_mov_b32 s31, s85
	s_nop 0
	v_addc_co_u32_e32 v149, vcc, 0, v75, vcc
	v_add_co_u32_e32 v150, vcc, 0x1000000, v74
	s_lshl_b64 s[4:5], s[30:31], 13
	s_nop 0
	v_addc_co_u32_e32 v151, vcc, 0, v75, vcc
	v_add_co_u32_e32 v152, vcc, 0x1800000, v74
	v_lshl_add_u64 v[72:73], v[68:69], 0, s[4:5]
	s_nop 0
	v_addc_co_u32_e32 v153, vcc, 0, v75, vcc
	v_add_co_u32_e32 v154, vcc, 0x2000000, v74
	s_nop 1
	v_addc_co_u32_e32 v155, vcc, 0, v75, vcc
	v_add_co_u32_e32 v156, vcc, 0x2800000, v74
	s_nop 1
	v_addc_co_u32_e32 v157, vcc, 0, v75, vcc
	v_add_co_u32_e32 v158, vcc, 0x3000000, v74
	s_nop 1
	v_addc_co_u32_e32 v159, vcc, 0, v75, vcc
	v_add_co_u32_e32 v162, vcc, 0x3800000, v74
	s_nop 1
	v_addc_co_u32_e32 v163, vcc, 0, v75, vcc
	global_load_dwordx4 v[84:87], v[74:75], off nt
	global_load_dwordx4 v[88:91], v[74:75], off offset:1024 nt
	global_load_dwordx4 v[92:95], v[148:149], off nt
	global_load_dwordx4 v[96:99], v[148:149], off offset:1024 nt
	global_load_dwordx4 v[100:103], v[150:151], off nt
	global_load_dwordx4 v[104:107], v[150:151], off offset:1024 nt
	global_load_dwordx4 v[108:111], v[152:153], off nt
	global_load_dwordx4 v[112:115], v[152:153], off offset:1024 nt
	global_load_dwordx4 v[116:119], v[154:155], off nt
	global_load_dwordx4 v[120:123], v[154:155], off offset:1024 nt
	global_load_dwordx4 v[124:127], v[156:157], off nt
	global_load_dwordx4 v[128:131], v[156:157], off offset:1024 nt
	global_load_dwordx4 v[132:135], v[158:159], off nt
	global_load_dwordx4 v[136:139], v[158:159], off offset:1024 nt
	global_load_dwordx4 v[140:143], v[162:163], off nt
	global_load_dwordx4 v[144:147], v[162:163], off offset:1024 nt
	s_waitcnt vmcnt(13)
	v_pk_add_f32 v[86:87], v[86:87], v[94:95]
	v_pk_add_f32 v[84:85], v[84:85], v[92:93]
	s_waitcnt vmcnt(9)
	v_pk_add_f32 v[92:93], v[102:103], v[110:111]
	v_pk_add_f32 v[94:95], v[100:101], v[108:109]
	v_pk_add_f32 v[92:93], v[86:87], v[92:93]
	v_pk_add_f32 v[94:95], v[84:85], v[94:95]
	s_waitcnt vmcnt(5)
	v_pk_add_f32 v[84:85], v[118:119], v[126:127]
	s_waitcnt vmcnt(1)
	v_pk_add_f32 v[86:87], v[134:135], v[142:143]
	v_pk_add_f32 v[100:101], v[116:117], v[124:125]
	v_pk_add_f32 v[108:109], v[84:85], v[86:87]
	ds_read_b128 v[84:87], v76
	v_pk_add_f32 v[102:103], v[132:133], v[140:141]
	s_nop 0
	v_pk_add_f32 v[100:101], v[100:101], v[102:103]
	v_pk_add_f32 v[102:103], v[92:93], v[108:109]
	v_pk_add_f32 v[100:101], v[94:95], v[100:101]
	ds_read_b128 v[92:95], v76 offset:1024
	s_waitcnt lgkmcnt(1)
	v_pk_fma_f32 v[62:63], v[102:103], v[86:87], v[62:63]
	v_pk_fma_f32 v[60:61], v[100:101], v[84:85], v[60:61]
	v_pk_add_f32 v[84:85], v[90:91], v[98:99]
	v_pk_add_f32 v[86:87], v[88:89], v[96:97]
	v_pk_add_f32 v[88:89], v[106:107], v[114:115]
	v_pk_add_f32 v[90:91], v[104:105], v[112:113]
	v_pk_add_f32 v[84:85], v[84:85], v[88:89]
	v_pk_add_f32 v[86:87], v[86:87], v[90:91]
	v_pk_add_f32 v[88:89], v[122:123], v[130:131]
	v_pk_add_f32 v[90:91], v[120:121], v[128:129]
	s_waitcnt vmcnt(0)
	v_pk_add_f32 v[96:97], v[138:139], v[146:147]
	v_pk_add_f32 v[98:99], v[136:137], v[144:145]
	v_pk_add_f32 v[88:89], v[88:89], v[96:97]
	v_pk_add_f32 v[90:91], v[90:91], v[98:99]
	v_pk_add_f32 v[84:85], v[84:85], v[88:89]
	v_pk_add_f32 v[86:87], v[86:87], v[90:91]
	s_waitcnt lgkmcnt(0)
	v_pk_fma_f32 v[58:59], v[84:85], v[94:95], v[58:59]
	v_pk_fma_f32 v[56:57], v[86:87], v[92:93], v[56:57]
	global_store_dwordx4 v[72:73], v[60:63], off
	global_store_dwordx4 v[72:73], v[56:59], off offset:1024
	global_load_dwordx4 v[84:87], v[74:75], off offset:2048 nt
	global_load_dwordx4 v[88:91], v[74:75], off offset:3072 nt
	global_load_dwordx4 v[92:95], v[148:149], off offset:2048 nt
	global_load_dwordx4 v[96:99], v[148:149], off offset:3072 nt
	global_load_dwordx4 v[100:103], v[150:151], off offset:2048 nt
	global_load_dwordx4 v[104:107], v[150:151], off offset:3072 nt
	global_load_dwordx4 v[108:111], v[152:153], off offset:2048 nt
	global_load_dwordx4 v[112:115], v[152:153], off offset:3072 nt
	global_load_dwordx4 v[116:119], v[154:155], off offset:2048 nt
	global_load_dwordx4 v[120:123], v[154:155], off offset:3072 nt
	global_load_dwordx4 v[124:127], v[156:157], off offset:2048 nt
	global_load_dwordx4 v[128:131], v[156:157], off offset:3072 nt
	global_load_dwordx4 v[132:135], v[158:159], off offset:2048 nt
	global_load_dwordx4 v[136:139], v[158:159], off offset:3072 nt
	global_load_dwordx4 v[140:143], v[162:163], off offset:2048 nt
	global_load_dwordx4 v[144:147], v[162:163], off offset:3072 nt
	s_waitcnt vmcnt(13)
	v_pk_add_f32 v[86:87], v[86:87], v[94:95]
	v_pk_add_f32 v[84:85], v[84:85], v[92:93]
	s_waitcnt vmcnt(9)
; __device__ __forceinline__ void norm_mod_phase(const Frame& F0, const Args& a0, int l, int which, bool skip_ctx, const float* slabgate) {
;     ...
;         if (slabgate != nullptr && m >= 8192) {
;             const f32x4* sl = (const f32x4*)((const float*)(a.ws + WS_SLAB) + (size_t)(m - 8192) * DM) + F.lane;
; #pragma unroll
;             for (int jp = 0; jp < 4; ++jp) {
;                 f32x4 sv[2][8];
; #pragma unroll
;                 for (int jj = 0; jj < 2; ++jj)
; #pragma unroll
;                     for (int ks = 0; ks < 8; ++ks) sv[jj][ks] = sl[(size_t)ks * 1024 * (DM / 4) + 64 * (2 * jp + jj)];
;                 __builtin_amdgcn_sched_barrier(0);
; #pragma unroll
;                 for (int jj = 0; jj < 2; ++jj) { const int j = 2 * jp + jj;
;                     const f32x4 sum = ((sv[jj][0] + sv[jj][1]) + (sv[jj][2] + sv[jj][3])) + ((sv[jj][4] + sv[jj][5]) + (sv[jj][6] + sv[jj][7]));
;                     v[j] = v[j] + cg[F.lane + 64 * j] * sum;
;                     ((f32x4*)(a.ws + WS_X) + (size_t)m * (DM / 4) + F.lane)[64 * j] = v[j]; }
;                 __builtin_amdgcn_sched_barrier(0);
;             }
	v_pk_add_f32 v[92:93], v[102:103], v[110:111]
	v_pk_add_f32 v[94:95], v[100:101], v[108:109]
	v_pk_add_f32 v[92:93], v[86:87], v[92:93]
	v_pk_add_f32 v[94:95], v[84:85], v[94:95]
	s_waitcnt vmcnt(5)
	v_pk_add_f32 v[84:85], v[118:119], v[126:127]
	s_waitcnt vmcnt(1)
	v_pk_add_f32 v[86:87], v[134:135], v[142:143]
	v_pk_add_f32 v[100:101], v[116:117], v[124:125]
	v_pk_add_f32 v[108:109], v[84:85], v[86:87]
	ds_read_b128 v[84:87], v76 offset:2048
	v_pk_add_f32 v[102:103], v[132:133], v[140:141]
	s_nop 0
	v_pk_add_f32 v[100:101], v[100:101], v[102:103]
	v_pk_add_f32 v[102:103], v[92:93], v[108:109]
	v_pk_add_f32 v[100:101], v[94:95], v[100:101]
	ds_read_b128 v[92:95], v76 offset:3072
	s_waitcnt lgkmcnt(1)
	v_pk_fma_f32 v[54:55], v[102:103], v[86:87], v[54:55]
	v_pk_fma_f32 v[52:53], v[100:101], v[84:85], v[52:53]
	v_pk_add_f32 v[84:85], v[90:91], v[98:99]
	v_pk_add_f32 v[86:87], v[88:89], v[96:97]
	v_pk_add_f32 v[88:89], v[106:107], v[114:115]
	v_pk_add_f32 v[90:91], v[104:105], v[112:113]
	v_pk_add_f32 v[84:85], v[84:85], v[88:89]
	v_pk_add_f32 v[86:87], v[86:87], v[90:91]
	v_pk_add_f32 v[88:89], v[122:123], v[130:131]
	v_pk_add_f32 v[90:91], v[120:121], v[128:129]
	s_waitcnt vmcnt(0)
	v_pk_add_f32 v[96:97], v[138:139], v[146:147]
	v_pk_add_f32 v[98:99], v[136:137], v[144:145]
	v_pk_add_f32 v[88:89], v[88:89], v[96:97]
	v_pk_add_f32 v[90:91], v[90:91], v[98:99]
	v_pk_add_f32 v[84:85], v[84:85], v[88:89]
	v_pk_add_f32 v[86:87], v[86:87], v[90:91]
	s_waitcnt lgkmcnt(0)
	v_pk_fma_f32 v[50:51], v[84:85], v[94:95], v[50:51]
	v_pk_fma_f32 v[48:49], v[86:87], v[92:93], v[48:49]
	global_store_dwordx4 v[72:73], v[52:55], off offset:2048
	global_store_dwordx4 v[72:73], v[48:51], off offset:3072
	s_movk_i32 s5, 0x1000
	v_add_co_u32_e32 v148, vcc, s5, v74
	s_mov_b32 s4, 0x1001000
	s_nop 0
	v_addc_co_u32_e32 v149, vcc, 0, v75, vcc
	v_add_co_u32_e32 v150, vcc, s37, v74
	s_nop 1
	v_addc_co_u32_e32 v151, vcc, 0, v75, vcc
	v_add_co_u32_e32 v152, vcc, s4, v74
	s_mov_b32 s4, 0x1801000
	s_nop 0
	v_addc_co_u32_e32 v153, vcc, 0, v75, vcc
	v_add_co_u32_e32 v154, vcc, s4, v74
	s_mov_b32 s4, 0x2001000
	s_nop 0
	v_addc_co_u32_e32 v155, vcc, 0, v75, vcc
	v_add_co_u32_e32 v156, vcc, s4, v74
	s_mov_b32 s4, 0x2801000
	s_nop 0
	v_addc_co_u32_e32 v157, vcc, 0, v75, vcc
	v_add_co_u32_e32 v158, vcc, s4, v74
	s_mov_b32 s4, 0x3001000
	s_nop 0
	v_addc_co_u32_e32 v159, vcc, 0, v75, vcc
	v_add_co_u32_e32 v162, vcc, s4, v74
	s_mov_b32 s4, 0x3801000
	s_nop 0
	v_addc_co_u32_e32 v163, vcc, 0, v75, vcc
	v_add_co_u32_e32 v164, vcc, s4, v74
	s_nop 1
	v_addc_co_u32_e32 v165, vcc, 0, v75, vcc
	global_load_dwordx4 v[84:87], v[148:149], off nt
	global_load_dwordx4 v[88:91], v[148:149], off offset:1024 nt
	global_load_dwordx4 v[92:95], v[150:151], off nt
	global_load_dwordx4 v[96:99], v[150:151], off offset:1024 nt
	global_load_dwordx4 v[100:103], v[152:153], off nt
	global_load_dwordx4 v[104:107], v[152:153], off offset:1024 nt
	global_load_dwordx4 v[108:111], v[154:155], off nt
	global_load_dwordx4 v[112:115], v[154:155], off offset:1024 nt
	global_load_dwordx4 v[116:119], v[156:157], off nt
	global_load_dwordx4 v[120:123], v[156:157], off offset:1024 nt
	global_load_dwordx4 v[124:127], v[158:159], off nt
	global_load_dwordx4 v[128:131], v[158:159], off offset:1024 nt
	global_load_dwordx4 v[132:135], v[162:163], off nt
	global_load_dwordx4 v[136:139], v[162:163], off offset:1024 nt
	global_load_dwordx4 v[140:143], v[164:165], off nt
	global_load_dwordx4 v[144:147], v[164:165], off offset:1024 nt
	s_waitcnt vmcnt(13)
	v_pk_add_f32 v[74:75], v[86:87], v[94:95]
	v_pk_add_f32 v[84:85], v[84:85], v[92:93]
	s_waitcnt vmcnt(9)
	v_pk_add_f32 v[86:87], v[102:103], v[110:111]
	v_pk_add_f32 v[92:93], v[100:101], v[108:109]
	v_pk_add_f32 v[74:75], v[74:75], v[86:87]
	v_pk_add_f32 v[92:93], v[84:85], v[92:93]
	s_waitcnt vmcnt(5)
	v_pk_add_f32 v[84:85], v[118:119], v[126:127]
	s_waitcnt vmcnt(1)
; __device__ __forceinline__ void norm_mod_phase(const Frame& F0, const Args& a0, int l, int which, bool skip_ctx, const float* slabgate) {
;     ...
;         if (slabgate != nullptr && m >= 8192) {
;             const f32x4* sl = (const f32x4*)((const float*)(a.ws + WS_SLAB) + (size_t)(m - 8192) * DM) + F.lane;
; #pragma unroll
;             for (int jp = 0; jp < 4; ++jp) {
;                 f32x4 sv[2][8];
; #pragma unroll
;                 for (int jj = 0; jj < 2; ++jj)
; #pragma unroll
;                     for (int ks = 0; ks < 8; ++ks) sv[jj][ks] = sl[(size_t)ks * 1024 * (DM / 4) + 64 * (2 * jp + jj)];
;                 __builtin_amdgcn_sched_barrier(0);
; #pragma unroll
;                 for (int jj = 0; jj < 2; ++jj) { const int j = 2 * jp + jj;
;                     const f32x4 sum = ((sv[jj][0] + sv[jj][1]) + (sv[jj][2] + sv[jj][3])) + ((sv[jj][4] + sv[jj][5]) + (sv[jj][6] + sv[jj][7]));
;                     v[j] = v[j] + cg[F.lane + 64 * j] * sum;
;                     ((f32x4*)(a.ws + WS_X) + (size_t)m * (DM / 4) + F.lane)[64 * j] = v[j]; }
;                 __builtin_amdgcn_sched_barrier(0);
;             }
	v_pk_add_f32 v[86:87], v[134:135], v[142:143]
	v_pk_add_f32 v[94:95], v[116:117], v[124:125]
	v_pk_add_f32 v[102:103], v[84:85], v[86:87]
	ds_read_b128 v[84:87], v76 offset:4096
	v_pk_add_f32 v[100:101], v[132:133], v[140:141]
	v_pk_add_f32 v[74:75], v[74:75], v[102:103]
	v_pk_add_f32 v[94:95], v[94:95], v[100:101]
	v_add_co_u32_e32 v166, vcc, s5, v72
	v_pk_add_f32 v[100:101], v[92:93], v[94:95]
	ds_read_b128 v[92:95], v76 offset:5120
	s_waitcnt lgkmcnt(1)
	v_pk_fma_f32 v[46:47], v[74:75], v[86:87], v[46:47]
	v_pk_fma_f32 v[44:45], v[100:101], v[84:85], v[44:45]
	v_addc_co_u32_e32 v167, vcc, 0, v73, vcc
	v_pk_add_f32 v[72:73], v[90:91], v[98:99]
	v_pk_add_f32 v[74:75], v[88:89], v[96:97]
	v_pk_add_f32 v[84:85], v[106:107], v[114:115]
	v_pk_add_f32 v[86:87], v[104:105], v[112:113]
	v_pk_add_f32 v[72:73], v[72:73], v[84:85]
	v_pk_add_f32 v[74:75], v[74:75], v[86:87]
	v_pk_add_f32 v[84:85], v[122:123], v[130:131]
	v_pk_add_f32 v[86:87], v[120:121], v[128:129]
	s_waitcnt vmcnt(0)
	v_pk_add_f32 v[88:89], v[138:139], v[146:147]
	v_pk_add_f32 v[90:91], v[136:137], v[144:145]
	v_pk_add_f32 v[84:85], v[84:85], v[88:89]
	v_pk_add_f32 v[86:87], v[86:87], v[90:91]
	v_pk_add_f32 v[72:73], v[72:73], v[84:85]
	v_pk_add_f32 v[74:75], v[74:75], v[86:87]
	s_waitcnt lgkmcnt(0)
	v_pk_fma_f32 v[42:43], v[72:73], v[94:95], v[42:43]
	v_pk_fma_f32 v[40:41], v[74:75], v[92:93], v[40:41]
	global_store_dwordx4 v[166:167], v[44:47], off
	global_store_dwordx4 v[166:167], v[40:43], off offset:1024
	global_load_dwordx4 v[72:75], v[148:149], off offset:2048 nt
	global_load_dwordx4 v[84:87], v[148:149], off offset:3072 nt
	global_load_dwordx4 v[88:91], v[150:151], off offset:2048 nt
	global_load_dwordx4 v[92:95], v[150:151], off offset:3072 nt
	global_load_dwordx4 v[96:99], v[152:153], off offset:2048 nt
	global_load_dwordx4 v[100:103], v[152:153], off offset:3072 nt
	global_load_dwordx4 v[104:107], v[154:155], off offset:2048 nt
	global_load_dwordx4 v[108:111], v[154:155], off offset:3072 nt
	global_load_dwordx4 v[112:115], v[156:157], off offset:2048 nt
	global_load_dwordx4 v[116:119], v[156:157], off offset:3072 nt
	global_load_dwordx4 v[120:123], v[158:159], off offset:2048 nt
	global_load_dwordx4 v[124:127], v[158:159], off offset:3072 nt
	global_load_dwordx4 v[128:131], v[162:163], off offset:2048 nt
	global_load_dwordx4 v[132:135], v[162:163], off offset:3072 nt
	global_load_dwordx4 v[136:139], v[164:165], off offset:2048 nt
	global_load_dwordx4 v[140:143], v[164:165], off offset:3072 nt
	s_waitcnt vmcnt(13)
	v_pk_add_f32 v[74:75], v[74:75], v[90:91]
	v_pk_add_f32 v[72:73], v[72:73], v[88:89]
	s_waitcnt vmcnt(9)
	v_pk_add_f32 v[88:89], v[98:99], v[106:107]
	v_pk_add_f32 v[90:91], v[96:97], v[104:105]
	v_pk_add_f32 v[88:89], v[74:75], v[88:89]
	v_pk_add_f32 v[90:91], v[72:73], v[90:91]
	s_waitcnt vmcnt(5)
	v_pk_add_f32 v[72:73], v[114:115], v[122:123]
	s_waitcnt vmcnt(1)
	v_pk_add_f32 v[74:75], v[130:131], v[138:139]
	v_pk_add_f32 v[96:97], v[112:113], v[120:121]
	v_pk_add_f32 v[104:105], v[72:73], v[74:75]
	ds_read_b128 v[72:75], v76 offset:6144
	v_pk_add_f32 v[98:99], v[128:129], v[136:137]
	s_nop 0
	v_pk_add_f32 v[96:97], v[96:97], v[98:99]
	v_pk_add_f32 v[98:99], v[88:89], v[104:105]
	v_pk_add_f32 v[96:97], v[90:91], v[96:97]
	ds_read_b128 v[88:91], v76 offset:7168
	s_waitcnt lgkmcnt(1)
	v_pk_fma_f32 v[6:7], v[98:99], v[74:75], v[6:7]
	v_pk_fma_f32 v[4:5], v[96:97], v[72:73], v[4:5]
	v_pk_add_f32 v[72:73], v[86:87], v[94:95]
	v_pk_add_f32 v[74:75], v[84:85], v[92:93]
	v_pk_add_f32 v[84:85], v[102:103], v[110:111]
	v_pk_add_f32 v[86:87], v[100:101], v[108:109]
	v_pk_add_f32 v[72:73], v[72:73], v[84:85]
	v_pk_add_f32 v[74:75], v[74:75], v[86:87]
	v_pk_add_f32 v[84:85], v[118:119], v[126:127]
	v_pk_add_f32 v[86:87], v[116:117], v[124:125]
	s_waitcnt vmcnt(0)
	v_pk_add_f32 v[92:93], v[134:135], v[142:143]
	v_pk_add_f32 v[94:95], v[132:133], v[140:141]
	v_pk_add_f32 v[84:85], v[84:85], v[92:93]
	v_pk_add_f32 v[86:87], v[86:87], v[94:95]
	v_pk_add_f32 v[72:73], v[72:73], v[84:85]
	v_pk_add_f32 v[74:75], v[74:75], v[86:87]
	s_waitcnt lgkmcnt(0)
	v_pk_fma_f32 v[2:3], v[72:73], v[90:91], v[2:3]
	v_pk_fma_f32 v[0:1], v[74:75], v[88:89], v[0:1]
	global_store_dwordx4 v[166:167], v[4:7], off offset:2048
	global_store_dwordx4 v[166:167], v[0:3], off offset:3072

; #define LAS __attribute__((address_space(3)))
; __device__ __forceinline__ void norm_mod_phase(const Frame& F0, const Args& a0, int l, int which, bool skip_ctx, const float* slabgate) {
;     const Frame F = relaunder(F0); const Args a = relaunder_args(a0);
;     const float* X = (const float*)(a.ws + WS_X); bf16* H = (bf16*)(a.ws + WS_H);
;     const float* gain = a.in[which ? I_NFFN : I_NMIX] + (size_t)l * DM;
;     const float* modl = (const float*)(a.ws + WS_MOD) + (size_t)l * 5 * D6;
;     const int gw = F.vcu * NWAVES + F.wave, NGW = F.G * NWAVES;
;     LAS f32x4* ca = (LAS f32x4*)(F.lds + RING_OFF); LAS f32x4* cb = ca + 5 * (DM / 4); LAS f32x4* cg = cb + 5 * (DM / 4);
;     { f32x4 g[5], sc[5], sh[5];
; #pragma unroll
;       for (int r = 0; r < 5; ++r) { const float* shift = modl + (size_t)r * D6 + (which ? 3 * DM : 0);
;           g[r] = ((const f32x4*)gain)[F.tid]; sc[r] = ((const f32x4*)(shift + DM))[F.tid]; sh[r] = ((const f32x4*)shift)[F.tid]; }
;       f32x4 gt4 = (f32x4){0.f, 0.f, 0.f, 0.f}; if (slabgate != nullptr) gt4 = ((const f32x4*)slabgate)[F.tid];
;       __builtin_amdgcn_sched_barrier(0);
; #pragma unroll
;       for (int r = 0; r < 5; ++r) { ca[r * (DM / 4) + F.tid] = g[r] * (sc[r] + 1.0f); cb[r * (DM / 4) + F.tid] = sh[r]; }
;       cg[F.tid] = gt4; }
; __global__ void __launch_bounds__(NTHREADS, 2) fwd(Args args) {
;     ...
;         if (IN(GP(l, 6))) for (int rep = 0; rep < REP_NORM; ++rep) norm_mod_phase(F, args, l, 1, last, (last || rep) ? nullptr : modl + 3 * D6 + 2 * DM);
.LBB0_893:
	s_cmp_le_i32 s64, s18
	s_cselect_b64 s[0:1], -1, 0
	s_and_b64 s[0:1], s[0:1], s[2:3]
	s_andn2_b64 vcc, exec, s[0:1]
	s_cbranch_vccnz .LBB0_909
	s_mov_b32 s8, s93
	s_mov_b32 s6, s94
	s_mov_b32 s5, s95
	s_mov_b32 s4, s92
	v_readlane_b32 s48, v221, 0
	v_mbcnt_lo_u32_b32 v64, -1, 0
	v_mbcnt_hi_u32_b32 v64, -1, v64
	v_readlane_b32 s49, v221, 1
	s_mov_b64 s[6:7], s[48:49]
	v_readlane_b32 s50, v221, 2
	v_readlane_b32 s51, v221, 3
	s_mov_b64 s[6:7], s[50:51]
	v_readlane_b32 s52, v221, 4
	v_readlane_b32 s53, v221, 5
	s_mov_b64 s[6:7], s[52:53]
	v_readlane_b32 s54, v221, 6
	v_readlane_b32 s55, v221, 7
	s_mov_b64 s[6:7], s[54:55]
	v_readlane_b32 s56, v221, 8
	v_readlane_b32 s57, v221, 9
	s_mov_b64 s[6:7], s[56:57]
	v_readlane_b32 s58, v221, 10
	v_readlane_b32 s59, v221, 11
	s_mov_b64 s[6:7], s[58:59]
	v_readlane_b32 s60, v221, 12
	v_readlane_b32 s61, v221, 13
	s_mov_b64 s[6:7], s[60:61]
	v_readlane_b32 s62, v221, 14
	v_readlane_b32 s63, v221, 15
	s_mov_b64 s[6:7], s[62:63]
	v_readlane_b32 s48, v221, 16
	v_readlane_b32 s49, v221, 17
	s_mov_b64 s[6:7], s[48:49]
	v_readlane_b32 s50, v221, 18
	v_readlane_b32 s51, v221, 19
	s_mov_b64 s[6:7], s[50:51]
	v_readlane_b32 s52, v221, 20
	v_readlane_b32 s53, v221, 21
	s_mov_b64 s[6:7], s[52:53]
	v_readlane_b32 s54, v221, 22
	v_readlane_b32 s55, v221, 23
	s_mov_b64 s[6:7], s[54:55]
	v_readlane_b32 s56, v221, 24
	v_readlane_b32 s57, v221, 25
	s_mov_b64 s[6:7], s[56:57]
	v_readlane_b32 s58, v221, 26
	v_readlane_b32 s59, v221, 27
	s_mov_b64 s[6:7], s[58:59]
	v_readlane_b32 s60, v221, 28
	v_readlane_b32 s61, v221, 29
	v_readlane_b32 s62, v221, 30
	v_readlane_b32 s63, v221, 31
	s_mov_b64 s[10:11], s[60:61]
	s_mov_b64 s[6:7], s[62:63]
	s_mov_b64 s[6:7], s[40:41]
	s_mov_b64 s[6:7], s[42:43]
	s_lshl_b64 s[2:3], s[24:25], 13
	s_mov_b64 s[6:7], s[44:45]
	s_add_u32 s2, s10, s2
	s_waitcnt vmcnt(0)
	v_lshl_add_u32 v48, s5, 6, v64
	s_mov_b64 s[6:7], s[46:47]
	s_addc_u32 s3, s11, s3
	v_readlane_b32 s9, v220, 21
	s_add_u32 s10, s6, s9
	v_readlane_b32 s9, v220, 22
	v_ashrrev_i32_e32 v49, 31, v48
	s_addc_u32 s11, s7, s9
	v_lshlrev_b64 v[4:5], 4, v[48:49]
	v_lshl_add_u64 v[0:1], s[2:3], 0, v[4:5]
	v_lshl_add_u64 v[32:33], s[10:11], 0, v[4:5]
	s_mov_b32 s2, 0x108000
	v_add_co_u32_e32 v4, vcc, s2, v32
	s_mov_b32 s2, 0x106000
	s_nop 0
	v_addc_co_u32_e32 v5, vcc, 0, v33, vcc
	v_add_co_u32_e32 v6, vcc, s2, v32
	s_mov_b32 s2, 0x114000
	s_nop 0
	v_addc_co_u32_e32 v7, vcc, 0, v33, vcc
	v_add_co_u32_e32 v8, vcc, s2, v32
	s_mov_b32 s2, 0x112000
	s_nop 0
	v_addc_co_u32_e32 v9, vcc, 0, v33, vcc
	v_add_co_u32_e32 v10, vcc, s2, v32
	s_mov_b32 s2, 0x120000
	s_nop 0
	v_addc_co_u32_e32 v11, vcc, 0, v33, vcc
	v_add_co_u32_e32 v20, vcc, s2, v32
	s_mov_b32 s2, 0x11e000
	s_nop 0
	v_addc_co_u32_e32 v21, vcc, 0, v33, vcc
	v_add_co_u32_e32 v22, vcc, s2, v32
	s_mov_b32 s2, 0x12c000
	s_nop 0
	v_addc_co_u32_e32 v23, vcc, 0, v33, vcc
	v_add_co_u32_e32 v24, vcc, s2, v32
	global_load_dwordx4 v[0:3], v[0:1], off nt
	s_nop 0
	v_addc_co_u32_e32 v25, vcc, 0, v33, vcc
	v_add_co_u32_e32 v26, vcc, 0x12a000, v32
	global_load_dwordx4 v[12:15], v[4:5], off nt
	s_nop 0
	global_load_dwordx4 v[4:7], v[6:7], off nt
	v_addc_co_u32_e32 v27, vcc, 0, v33, vcc
	v_add_co_u32_e32 v34, vcc, 0x138000, v32
	global_load_dwordx4 v[16:19], v[8:9], off nt
	s_nop 0
	global_load_dwordx4 v[8:11], v[10:11], off nt
	v_addc_co_u32_e32 v35, vcc, 0, v33, vcc
	v_add_co_u32_e32 v32, vcc, 0x136000, v32
	global_load_dwordx4 v[28:31], v[20:21], off nt
	s_nop 0
	global_load_dwordx4 v[20:23], v[22:23], off nt
	v_addc_co_u32_e32 v33, vcc, 0, v33, vcc
	global_load_dwordx4 v[36:39], v[24:25], off nt
	s_nop 0
	global_load_dwordx4 v[24:27], v[26:27], off nt
	s_nop 0
	global_load_dwordx4 v[44:47], v[34:35], off nt
	s_nop 0
	global_load_dwordx4 v[32:35], v[32:33], off nt
	v_mov_b32_e32 v40, 0
	v_cndmask_b32_e64 v41, 0, 1, s[80:81]
	v_cmp_ne_u32_e64 s[2:3], 1, v41
	s_andn2_b64 vcc, exec, s[80:81]
	v_mov_b32_e32 v41, v40
	v_mov_b32_e32 v42, v40
	v_mov_b32_e32 v43, v40
	s_cbranch_vccnz .LBB0_896
	v_readlane_b32 s10, v220, 23
	v_readlane_b32 s11, v220, 24
	s_nop 1
	v_lshl_add_u64 v[40:41], v[48:49], 4, s[10:11]
	v_add_co_u32_e32 v40, vcc, 0x28000, v40
	s_nop 1
	v_addc_co_u32_e32 v41, vcc, 0, v41, vcc
	global_load_dwordx4 v[40:43], v[40:41], off nt

; #define NM_NEXT(mm) do { while ((mm) < mlim && skip_ctx && ((mm) % TT) < CTXL) (mm) += mstep; } while (0)
; __device__ __forceinline__ void norm_mod_phase(const Frame& F0, const Args& a0, int l, int which, bool skip_ctx, const float* slabgate) {
;     ...
;     NM_NEXT(m);
;     f32x4 v[8], vn[8];
;     const bool fromin = (l == 0 && which == 0);
;     ...
;     if (m < mlim) { const f32x4* xr = NM_ROW(m);
; #pragma unroll
;         for (int j = 0; j < 8; ++j) v[j] = xr[64 * j]; }
.LBB0_899:
	s_cmp_lt_i32 s5, s10
	s_mul_hi_i32 s4, s5, 0x38e38e39
	s_cselect_b64 s[2:3], -1, 0
	s_lshr_b32 s8, s4, 31
	s_ashr_i32 s4, s4, 9
	s_add_i32 s4, s4, s8
	s_mulk_i32 s4, 0x900
	s_sub_i32 s4, s5, s4
	s_cmpk_lt_i32 s4, 0x100
	s_cselect_b64 s[8:9], -1, 0
	s_and_b64 s[8:9], s[2:3], s[8:9]
	s_and_b64 s[8:9], s[76:77], s[8:9]
	s_add_i32 s5, s5, s11
	s_and_b64 vcc, exec, s[8:9]
	s_cbranch_vccnz .LBB0_899
	s_andn2_b64 vcc, exec, s[2:3]
	s_cbranch_vccnz .LBB0_909
	s_sub_i32 s4, s5, s11
	s_add_u32 s2, s6, 0x18000000
	s_addc_u32 s3, s7, 0
	s_ashr_i32 s5, s4, 31
	s_lshl_b64 s[8:9], s[4:5], 13
	s_add_u32 s8, s2, s8
	v_ashrrev_i32_e32 v65, 31, v64
	s_addc_u32 s9, s3, s9
	v_lshlrev_b64 v[32:33], 4, v[64:65]
	v_lshl_add_u64 v[16:17], s[8:9], 0, v[32:33]
	s_movk_i32 s5, 0x1000
	v_add_co_u32_e32 v28, vcc, s5, v16
	global_load_dwordx4 v[0:3], v[16:17], off nt
	global_load_dwordx4 v[4:7], v[16:17], off offset:1024 nt
	global_load_dwordx4 v[8:11], v[16:17], off offset:2048 nt
	global_load_dwordx4 v[12:15], v[16:17], off offset:3072 nt
	v_addc_co_u32_e32 v29, vcc, 0, v17, vcc
	global_load_dwordx4 v[16:19], v[28:29], off nt
	global_load_dwordx4 v[20:23], v[28:29], off offset:1024 nt
	global_load_dwordx4 v[24:27], v[28:29], off offset:2048 nt
	s_nop 0
	global_load_dwordx4 v[28:31], v[28:29], off offset:3072 nt
	v_lshl_add_u64 v[34:35], s[6:7], 0, v[32:33]
	v_lshl_add_u64 v[68:69], s[2:3], 0, v[32:33]
	v_lshlrev_b32_e32 v32, 2, v64
	s_mov_b64 s[8:9], 0x50000000
	s_add_i32 s5, 0, 0x14000
	v_xor_b32_e32 v77, 4, v32
	v_xor_b32_e32 v78, 8, v32
	v_xor_b32_e32 v79, 16, v32
	v_xor_b32_e32 v80, 32, v32
	v_xor_b32_e32 v81, 64, v32
	v_xor_b32_e32 v82, 0x80, v32
	v_lshl_add_u64 v[32:33], v[64:65], 3, s[6:7]
	s_mov_b64 s[2:3], 0x1c800000
	v_lshl_add_u64 v[66:67], v[34:35], 0, s[8:9]
	v_lshl_add_u32 v76, v64, 4, s5
	v_lshl_add_u64 v[70:71], v[32:33], 0, s[2:3]
	s_branch .LBB0_903

; #define NM_NEXT(mm) do { while ((mm) < mlim && skip_ctx && ((mm) % TT) < CTXL) (mm) += mstep; } while (0)
; __device__ __forceinline__ void norm_mod_phase(const Frame& F0, const Args& a0, int l, int which, bool skip_ctx, const float* slabgate) {
;     ...
;     NM_NEXT(m);
;     f32x4 v[8], vn[8];
;     const bool fromin = (l == 0 && which == 0);
;     ...
;     if (m < mlim) { const f32x4* xr = NM_ROW(m);
; #pragma unroll
;         for (int j = 0; j < 8; ++j) v[j] = xr[64 * j]; }
;     while (m < mlim) {
;         int mn = m + mstep; NM_NEXT(mn);
;         if (mn < mlim) { const f32x4* xr = NM_ROW(mn);
; #pragma unroll
;             for (int j = 0; j < 8; ++j) vn[j] = xr[64 * j]; }
;         const int b = m / TT, t = m - b * TT; const int r = (t < CTXL) ? 4 : b;
;         float ss = 0.f;
;         if (slabgate != nullptr && m >= 8192) {
;             const f32x4* sl = (const f32x4*)((const float*)(a.ws + WS_SLAB) + (size_t)(m - 8192) * DM) + F.lane;
; #pragma unroll
;             for (int jp = 0; jp < 4; ++jp) {
;                 f32x4 sv[2][8];
; #pragma unroll
;                 for (int jj = 0; jj < 2; ++jj)
; #pragma unroll
;                     for (int ks = 0; ks < 8; ++ks) sv[jj][ks] = sl[(size_t)ks * 1024 * (DM / 4) + 64 * (2 * jp + jj)];
;                 __builtin_amdgcn_sched_barrier(0);
; #pragma unroll
;                 for (int jj = 0; jj < 2; ++jj) { const int j = 2 * jp + jj;
;                     const f32x4 sum = ((sv[jj][0] + sv[jj][1]) + (sv[jj][2] + sv[jj][3])) + ((sv[jj][4] + sv[jj][5]) + (sv[jj][6] + sv[jj][7]));
;                     v[j] = v[j] + cg[F.lane + 64 * j] * sum;
;                     ((f32x4*)(a.ws + WS_X) + (size_t)m * (DM / 4) + F.lane)[64 * j] = v[j]; }
.LBB0_904:
	s_add_i32 s4, s4, s11
	s_cmp_lt_i32 s4, s10
	s_cselect_b64 s[2:3], -1, 0
	s_cmp_ge_i32 s4, s10
	s_mul_hi_i32 s5, s4, 0x38e38e39
	s_cselect_b64 s[6:7], -1, 0
	s_lshr_b32 s9, s5, 31
	s_ashr_i32 s5, s5, 9
	s_add_i32 s5, s5, s9
	s_mulk_i32 s5, 0x900
	s_sub_i32 s5, s4, s5
	s_cmpk_lt_i32 s5, 0x100
	s_cselect_b64 s[12:13], -1, 0
	s_and_b64 s[12:13], s[2:3], s[12:13]
	s_and_b64 s[12:13], s[76:77], s[12:13]
	s_and_b64 vcc, exec, s[12:13]
	s_cbranch_vccnz .LBB0_904
	s_andn2_b64 vcc, exec, s[2:3]
	s_cbranch_vccnz .LBB0_907
	s_ashr_i32 s5, s4, 31
	s_lshl_b64 s[2:3], s[4:5], 13
	v_lshl_add_u64 v[16:17], v[68:69], 0, s[2:3]
	v_add_co_u32_e32 v28, vcc, 0x1000, v16
	global_load_dwordx4 v[0:3], v[16:17], off nt
	global_load_dwordx4 v[4:7], v[16:17], off offset:1024 nt
	global_load_dwordx4 v[8:11], v[16:17], off offset:2048 nt
	global_load_dwordx4 v[12:15], v[16:17], off offset:3072 nt
	v_addc_co_u32_e32 v29, vcc, 0, v17, vcc
	global_load_dwordx4 v[16:19], v[28:29], off nt
	global_load_dwordx4 v[20:23], v[28:29], off offset:1024 nt
	global_load_dwordx4 v[24:27], v[28:29], off offset:2048 nt
	s_nop 0
	global_load_dwordx4 v[28:31], v[28:29], off offset:3072 nt
.LBB0_907:
	s_cmpk_lt_i32 s8, 0x2000
	s_cselect_b64 s[2:3], -1, 0
	s_or_b64 s[2:3], s[76:77], s[2:3]
	s_and_b64 vcc, exec, s[2:3]
	s_cbranch_vccnz .LBB0_902
	s_add_i32 s84, s8, 0xffffe000
	s_lshl_b64 s[2:3], s[84:85], 13
	v_lshl_add_u64 v[74:75], v[66:67], 0, s[2:3]
	v_add_co_u32_e32 v148, vcc, 0x800000, v74
	s_mov_b32 s9, s85
	s_nop 0
	v_addc_co_u32_e32 v149, vcc, 0, v75, vcc
	v_add_co_u32_e32 v150, vcc, 0x1000000, v74
	s_lshl_b64 s[2:3], s[8:9], 13
	s_nop 0
	v_addc_co_u32_e32 v151, vcc, 0, v75, vcc
	v_add_co_u32_e32 v152, vcc, 0x1800000, v74
	v_lshl_add_u64 v[72:73], v[68:69], 0, s[2:3]
	s_nop 0
	v_addc_co_u32_e32 v153, vcc, 0, v75, vcc
	v_add_co_u32_e32 v154, vcc, 0x2000000, v74
	s_nop 1
	v_addc_co_u32_e32 v155, vcc, 0, v75, vcc
	v_add_co_u32_e32 v156, vcc, 0x2800000, v74
	s_nop 1
	v_addc_co_u32_e32 v157, vcc, 0, v75, vcc
	v_add_co_u32_e32 v158, vcc, 0x3000000, v74
	s_nop 1
	v_addc_co_u32_e32 v159, vcc, 0, v75, vcc
	v_add_co_u32_e32 v162, vcc, 0x3800000, v74
	s_nop 1
	v_addc_co_u32_e32 v163, vcc, 0, v75, vcc
	global_load_dwordx4 v[84:87], v[74:75], off nt
	global_load_dwordx4 v[88:91], v[74:75], off offset:1024 nt
	global_load_dwordx4 v[92:95], v[148:149], off nt
	global_load_dwordx4 v[96:99], v[148:149], off offset:1024 nt
	global_load_dwordx4 v[100:103], v[150:151], off nt
	global_load_dwordx4 v[104:107], v[150:151], off offset:1024 nt
	global_load_dwordx4 v[108:111], v[152:153], off nt
	global_load_dwordx4 v[112:115], v[152:153], off offset:1024 nt
	global_load_dwordx4 v[116:119], v[154:155], off nt
	global_load_dwordx4 v[120:123], v[154:155], off offset:1024 nt
	global_load_dwordx4 v[124:127], v[156:157], off nt
	global_load_dwordx4 v[128:131], v[156:157], off offset:1024 nt
	global_load_dwordx4 v[132:135], v[158:159], off nt
	global_load_dwordx4 v[136:139], v[158:159], off offset:1024 nt
	global_load_dwordx4 v[140:143], v[162:163], off nt
	global_load_dwordx4 v[144:147], v[162:163], off offset:1024 nt
	s_waitcnt vmcnt(13)
	v_pk_add_f32 v[86:87], v[86:87], v[94:95]
	v_pk_add_f32 v[84:85], v[84:85], v[92:93]
	s_waitcnt vmcnt(9)
	v_pk_add_f32 v[92:93], v[102:103], v[110:111]
	v_pk_add_f32 v[94:95], v[100:101], v[108:109]
	v_pk_add_f32 v[92:93], v[86:87], v[92:93]
	v_pk_add_f32 v[94:95], v[84:85], v[94:95]
	s_waitcnt vmcnt(5)
	v_pk_add_f32 v[84:85], v[118:119], v[126:127]
	s_waitcnt vmcnt(1)
	v_pk_add_f32 v[86:87], v[134:135], v[142:143]
	v_pk_add_f32 v[100:101], v[116:117], v[124:125]
	v_pk_add_f32 v[108:109], v[84:85], v[86:87]
	ds_read_b128 v[84:87], v76
	v_pk_add_f32 v[102:103], v[132:133], v[140:141]
	s_nop 0
	v_pk_add_f32 v[100:101], v[100:101], v[102:103]
	v_pk_add_f32 v[102:103], v[92:93], v[108:109]
	v_pk_add_f32 v[100:101], v[94:95], v[100:101]
	ds_read_b128 v[92:95], v76 offset:1024
	s_waitcnt lgkmcnt(1)
	v_pk_fma_f32 v[62:63], v[102:103], v[86:87], v[62:63]
	v_pk_fma_f32 v[60:61], v[100:101], v[84:85], v[60:61]
	v_pk_add_f32 v[84:85], v[90:91], v[98:99]
	v_pk_add_f32 v[86:87], v[88:89], v[96:97]
	v_pk_add_f32 v[88:89], v[106:107], v[114:115]
	v_pk_add_f32 v[90:91], v[104:105], v[112:113]
	v_pk_add_f32 v[84:85], v[84:85], v[88:89]
	v_pk_add_f32 v[86:87], v[86:87], v[90:91]
	v_pk_add_f32 v[88:89], v[122:123], v[130:131]
	v_pk_add_f32 v[90:91], v[120:121], v[128:129]
	s_waitcnt vmcnt(0)
	v_pk_add_f32 v[96:97], v[138:139], v[146:147]
	v_pk_add_f32 v[98:99], v[136:137], v[144:145]
	v_pk_add_f32 v[88:89], v[88:89], v[96:97]
	v_pk_add_f32 v[90:91], v[90:91], v[98:99]
	v_pk_add_f32 v[84:85], v[84:85], v[88:89]
	v_pk_add_f32 v[86:87], v[86:87], v[90:91]
	s_waitcnt lgkmcnt(0)
	v_pk_fma_f32 v[58:59], v[84:85], v[94:95], v[58:59]
	v_pk_fma_f32 v[56:57], v[86:87], v[92:93], v[56:57]
	global_store_dwordx4 v[72:73], v[60:63], off
	global_store_dwordx4 v[72:73], v[56:59], off offset:1024
	global_load_dwordx4 v[84:87], v[74:75], off offset:2048 nt
	global_load_dwordx4 v[88:91], v[74:75], off offset:3072 nt
	global_load_dwordx4 v[92:95], v[148:149], off offset:2048 nt
	global_load_dwordx4 v[96:99], v[148:149], off offset:3072 nt
	global_load_dwordx4 v[100:103], v[150:151], off offset:2048 nt
	global_load_dwordx4 v[104:107], v[150:151], off offset:3072 nt
	global_load_dwordx4 v[108:111], v[152:153], off offset:2048 nt
	global_load_dwordx4 v[112:115], v[152:153], off offset:3072 nt
	global_load_dwordx4 v[116:119], v[154:155], off offset:2048 nt
	global_load_dwordx4 v[120:123], v[154:155], off offset:3072 nt
	global_load_dwordx4 v[124:127], v[156:157], off offset:2048 nt
	global_load_dwordx4 v[128:131], v[156:157], off offset:3072 nt
	global_load_dwordx4 v[132:135], v[158:159], off offset:2048 nt
	global_load_dwordx4 v[136:139], v[158:159], off offset:3072 nt
	global_load_dwordx4 v[140:143], v[162:163], off offset:2048 nt
	global_load_dwordx4 v[144:147], v[162:163], off offset:3072 nt
	s_waitcnt vmcnt(13)
; __device__ __forceinline__ void norm_mod_phase(const Frame& F0, const Args& a0, int l, int which, bool skip_ctx, const float* slabgate) {
;     ...
;             for (int jp = 0; jp < 4; ++jp) {
;                 f32x4 sv[2][8];
; #pragma unroll
;                 for (int jj = 0; jj < 2; ++jj)
; #pragma unroll
;                     for (int ks = 0; ks < 8; ++ks) sv[jj][ks] = sl[(size_t)ks * 1024 * (DM / 4) + 64 * (2 * jp + jj)];
;                 __builtin_amdgcn_sched_barrier(0);
; #pragma unroll
;                 for (int jj = 0; jj < 2; ++jj) { const int j = 2 * jp + jj;
;                     const f32x4 sum = ((sv[jj][0] + sv[jj][1]) + (sv[jj][2] + sv[jj][3])) + ((sv[jj][4] + sv[jj][5]) + (sv[jj][6] + sv[jj][7]));
;                     v[j] = v[j] + cg[F.lane + 64 * j] * sum;
;                     ((f32x4*)(a.ws + WS_X) + (size_t)m * (DM / 4) + F.lane)[64 * j] = v[j]; }
;                 __builtin_amdgcn_sched_barrier(0);
	v_pk_add_f32 v[86:87], v[86:87], v[94:95]
	v_pk_add_f32 v[84:85], v[84:85], v[92:93]
	s_waitcnt vmcnt(9)
	v_pk_add_f32 v[92:93], v[102:103], v[110:111]
	v_pk_add_f32 v[94:95], v[100:101], v[108:109]
	v_pk_add_f32 v[92:93], v[86:87], v[92:93]
	v_pk_add_f32 v[94:95], v[84:85], v[94:95]
	s_waitcnt vmcnt(5)
	v_pk_add_f32 v[84:85], v[118:119], v[126:127]
	s_waitcnt vmcnt(1)
	v_pk_add_f32 v[86:87], v[134:135], v[142:143]
	v_pk_add_f32 v[100:101], v[116:117], v[124:125]
	v_pk_add_f32 v[108:109], v[84:85], v[86:87]
	ds_read_b128 v[84:87], v76 offset:2048
	v_pk_add_f32 v[102:103], v[132:133], v[140:141]
	s_nop 0
	v_pk_add_f32 v[100:101], v[100:101], v[102:103]
	v_pk_add_f32 v[102:103], v[92:93], v[108:109]
	v_pk_add_f32 v[100:101], v[94:95], v[100:101]
	ds_read_b128 v[92:95], v76 offset:3072
	s_waitcnt lgkmcnt(1)
	v_pk_fma_f32 v[54:55], v[102:103], v[86:87], v[54:55]
	v_pk_fma_f32 v[52:53], v[100:101], v[84:85], v[52:53]
	v_pk_add_f32 v[84:85], v[90:91], v[98:99]
	v_pk_add_f32 v[86:87], v[88:89], v[96:97]
	v_pk_add_f32 v[88:89], v[106:107], v[114:115]
	v_pk_add_f32 v[90:91], v[104:105], v[112:113]
	v_pk_add_f32 v[84:85], v[84:85], v[88:89]
	v_pk_add_f32 v[86:87], v[86:87], v[90:91]
	v_pk_add_f32 v[88:89], v[122:123], v[130:131]
	v_pk_add_f32 v[90:91], v[120:121], v[128:129]
	s_waitcnt vmcnt(0)
	v_pk_add_f32 v[96:97], v[138:139], v[146:147]
	v_pk_add_f32 v[98:99], v[136:137], v[144:145]
	v_pk_add_f32 v[88:89], v[88:89], v[96:97]
	v_pk_add_f32 v[90:91], v[90:91], v[98:99]
	v_pk_add_f32 v[84:85], v[84:85], v[88:89]
	v_pk_add_f32 v[86:87], v[86:87], v[90:91]
	s_waitcnt lgkmcnt(0)
	v_pk_fma_f32 v[50:51], v[84:85], v[94:95], v[50:51]
	v_pk_fma_f32 v[48:49], v[86:87], v[92:93], v[48:49]
	global_store_dwordx4 v[72:73], v[52:55], off offset:2048
	global_store_dwordx4 v[72:73], v[48:51], off offset:3072
	s_movk_i32 s3, 0x1000
	v_add_co_u32_e32 v148, vcc, s3, v74
	s_mov_b32 s2, 0x1001000
	s_nop 0
	v_addc_co_u32_e32 v149, vcc, 0, v75, vcc
	v_add_co_u32_e32 v150, vcc, s37, v74
	s_nop 1
	v_addc_co_u32_e32 v151, vcc, 0, v75, vcc
	v_add_co_u32_e32 v152, vcc, s2, v74
	s_mov_b32 s2, 0x1801000
	s_nop 0
	v_addc_co_u32_e32 v153, vcc, 0, v75, vcc
	v_add_co_u32_e32 v154, vcc, s2, v74
	s_mov_b32 s2, 0x2001000
	s_nop 0
	v_addc_co_u32_e32 v155, vcc, 0, v75, vcc
	v_add_co_u32_e32 v156, vcc, s2, v74
	s_mov_b32 s2, 0x2801000
	s_nop 0
	v_addc_co_u32_e32 v157, vcc, 0, v75, vcc
	v_add_co_u32_e32 v158, vcc, s2, v74
	s_mov_b32 s2, 0x3001000
	s_nop 0
	v_addc_co_u32_e32 v159, vcc, 0, v75, vcc
	v_add_co_u32_e32 v162, vcc, s2, v74
	s_mov_b32 s2, 0x3801000
	s_nop 0
	v_addc_co_u32_e32 v163, vcc, 0, v75, vcc
	v_add_co_u32_e32 v164, vcc, s2, v74
	s_nop 1
	v_addc_co_u32_e32 v165, vcc, 0, v75, vcc
	global_load_dwordx4 v[84:87], v[148:149], off nt
	global_load_dwordx4 v[88:91], v[148:149], off offset:1024 nt
	global_load_dwordx4 v[92:95], v[150:151], off nt
	global_load_dwordx4 v[96:99], v[150:151], off offset:1024 nt
	global_load_dwordx4 v[100:103], v[152:153], off nt
	global_load_dwordx4 v[104:107], v[152:153], off offset:1024 nt
	global_load_dwordx4 v[108:111], v[154:155], off nt
	global_load_dwordx4 v[112:115], v[154:155], off offset:1024 nt
	global_load_dwordx4 v[116:119], v[156:157], off nt
	global_load_dwordx4 v[120:123], v[156:157], off offset:1024 nt
	global_load_dwordx4 v[124:127], v[158:159], off nt
	global_load_dwordx4 v[128:131], v[158:159], off offset:1024 nt
	global_load_dwordx4 v[132:135], v[162:163], off nt
	global_load_dwordx4 v[136:139], v[162:163], off offset:1024 nt
	global_load_dwordx4 v[140:143], v[164:165], off nt
	global_load_dwordx4 v[144:147], v[164:165], off offset:1024 nt
	s_waitcnt vmcnt(13)
	v_pk_add_f32 v[74:75], v[86:87], v[94:95]
	v_pk_add_f32 v[84:85], v[84:85], v[92:93]
	s_waitcnt vmcnt(9)
	v_pk_add_f32 v[86:87], v[102:103], v[110:111]
	v_pk_add_f32 v[92:93], v[100:101], v[108:109]
	v_pk_add_f32 v[74:75], v[74:75], v[86:87]
	v_pk_add_f32 v[92:93], v[84:85], v[92:93]
	s_waitcnt vmcnt(5)
	v_pk_add_f32 v[84:85], v[118:119], v[126:127]
	s_waitcnt vmcnt(1)
; __device__ __forceinline__ void norm_mod_phase(const Frame& F0, const Args& a0, int l, int which, bool skip_ctx, const float* slabgate) {
;     ...
;             for (int jp = 0; jp < 4; ++jp) {
;                 f32x4 sv[2][8];
; #pragma unroll
;                 for (int jj = 0; jj < 2; ++jj)
; #pragma unroll
;                     for (int ks = 0; ks < 8; ++ks) sv[jj][ks] = sl[(size_t)ks * 1024 * (DM / 4) + 64 * (2 * jp + jj)];
;                 __builtin_amdgcn_sched_barrier(0);
; #pragma unroll
;                 for (int jj = 0; jj < 2; ++jj) { const int j = 2 * jp + jj;
;                     const f32x4 sum = ((sv[jj][0] + sv[jj][1]) + (sv[jj][2] + sv[jj][3])) + ((sv[jj][4] + sv[jj][5]) + (sv[jj][6] + sv[jj][7]));
;                     v[j] = v[j] + cg[F.lane + 64 * j] * sum;
;                     ((f32x4*)(a.ws + WS_X) + (size_t)m * (DM / 4) + F.lane)[64 * j] = v[j]; }
;                 __builtin_amdgcn_sched_barrier(0);
	v_pk_add_f32 v[86:87], v[134:135], v[142:143]
	v_pk_add_f32 v[94:95], v[116:117], v[124:125]
	v_pk_add_f32 v[102:103], v[84:85], v[86:87]
	ds_read_b128 v[84:87], v76 offset:4096
	v_pk_add_f32 v[100:101], v[132:133], v[140:141]
	v_pk_add_f32 v[74:75], v[74:75], v[102:103]
	v_pk_add_f32 v[94:95], v[94:95], v[100:101]
	v_add_co_u32_e32 v166, vcc, s3, v72
	v_pk_add_f32 v[100:101], v[92:93], v[94:95]
	ds_read_b128 v[92:95], v76 offset:5120
	s_waitcnt lgkmcnt(1)
	v_pk_fma_f32 v[46:47], v[74:75], v[86:87], v[46:47]
	v_pk_fma_f32 v[44:45], v[100:101], v[84:85], v[44:45]
	v_addc_co_u32_e32 v167, vcc, 0, v73, vcc
	v_pk_add_f32 v[72:73], v[90:91], v[98:99]
	v_pk_add_f32 v[74:75], v[88:89], v[96:97]
	v_pk_add_f32 v[84:85], v[106:107], v[114:115]
	v_pk_add_f32 v[86:87], v[104:105], v[112:113]
	v_pk_add_f32 v[72:73], v[72:73], v[84:85]
	v_pk_add_f32 v[74:75], v[74:75], v[86:87]
	v_pk_add_f32 v[84:85], v[122:123], v[130:131]
	v_pk_add_f32 v[86:87], v[120:121], v[128:129]
	s_waitcnt vmcnt(0)
	v_pk_add_f32 v[88:89], v[138:139], v[146:147]
	v_pk_add_f32 v[90:91], v[136:137], v[144:145]
	v_pk_add_f32 v[84:85], v[84:85], v[88:89]
	v_pk_add_f32 v[86:87], v[86:87], v[90:91]
	v_pk_add_f32 v[72:73], v[72:73], v[84:85]
	v_pk_add_f32 v[74:75], v[74:75], v[86:87]
	s_waitcnt lgkmcnt(0)
	v_pk_fma_f32 v[42:43], v[72:73], v[94:95], v[42:43]
	v_pk_fma_f32 v[40:41], v[74:75], v[92:93], v[40:41]
	global_store_dwordx4 v[166:167], v[44:47], off
	global_store_dwordx4 v[166:167], v[40:43], off offset:1024
	global_load_dwordx4 v[72:75], v[148:149], off offset:2048 nt
	global_load_dwordx4 v[84:87], v[148:149], off offset:3072 nt
	global_load_dwordx4 v[88:91], v[150:151], off offset:2048 nt
	global_load_dwordx4 v[92:95], v[150:151], off offset:3072 nt
	global_load_dwordx4 v[96:99], v[152:153], off offset:2048 nt
	global_load_dwordx4 v[100:103], v[152:153], off offset:3072 nt
	global_load_dwordx4 v[104:107], v[154:155], off offset:2048 nt
	global_load_dwordx4 v[108:111], v[154:155], off offset:3072 nt
	global_load_dwordx4 v[112:115], v[156:157], off offset:2048 nt
	global_load_dwordx4 v[116:119], v[156:157], off offset:3072 nt
	global_load_dwordx4 v[120:123], v[158:159], off offset:2048 nt
	global_load_dwordx4 v[124:127], v[158:159], off offset:3072 nt
	global_load_dwordx4 v[128:131], v[162:163], off offset:2048 nt
	global_load_dwordx4 v[132:135], v[162:163], off offset:3072 nt
	global_load_dwordx4 v[136:139], v[164:165], off offset:2048 nt
	global_load_dwordx4 v[140:143], v[164:165], off offset:3072 nt
	s_waitcnt vmcnt(13)
	v_pk_add_f32 v[74:75], v[74:75], v[90:91]
	v_pk_add_f32 v[72:73], v[72:73], v[88:89]
	s_waitcnt vmcnt(9)
	v_pk_add_f32 v[88:89], v[98:99], v[106:107]
	v_pk_add_f32 v[90:91], v[96:97], v[104:105]
	v_pk_add_f32 v[88:89], v[74:75], v[88:89]
	v_pk_add_f32 v[90:91], v[72:73], v[90:91]
	s_waitcnt vmcnt(5)
	v_pk_add_f32 v[72:73], v[114:115], v[122:123]
	s_waitcnt vmcnt(1)
	v_pk_add_f32 v[74:75], v[130:131], v[138:139]
	v_pk_add_f32 v[96:97], v[112:113], v[120:121]
	v_pk_add_f32 v[104:105], v[72:73], v[74:75]
	ds_read_b128 v[72:75], v76 offset:6144
	v_pk_add_f32 v[98:99], v[128:129], v[136:137]
	s_nop 0
	v_pk_add_f32 v[96:97], v[96:97], v[98:99]
	v_pk_add_f32 v[98:99], v[88:89], v[104:105]
	v_pk_add_f32 v[96:97], v[90:91], v[96:97]
	ds_read_b128 v[88:91], v76 offset:7168
	s_waitcnt lgkmcnt(1)
	v_pk_fma_f32 v[38:39], v[98:99], v[74:75], v[38:39]
	v_pk_fma_f32 v[36:37], v[96:97], v[72:73], v[36:37]
	v_pk_add_f32 v[72:73], v[86:87], v[94:95]
	v_pk_add_f32 v[74:75], v[84:85], v[92:93]
	v_pk_add_f32 v[84:85], v[102:103], v[110:111]
	v_pk_add_f32 v[86:87], v[100:101], v[108:109]
	v_pk_add_f32 v[72:73], v[72:73], v[84:85]
	v_pk_add_f32 v[74:75], v[74:75], v[86:87]
	v_pk_add_f32 v[84:85], v[118:119], v[126:127]
	v_pk_add_f32 v[86:87], v[116:117], v[124:125]
	s_waitcnt vmcnt(0)
	v_pk_add_f32 v[92:93], v[134:135], v[142:143]
	v_pk_add_f32 v[94:95], v[132:133], v[140:141]
	v_pk_add_f32 v[84:85], v[84:85], v[92:93]
	v_pk_add_f32 v[86:87], v[86:87], v[94:95]
	v_pk_add_f32 v[72:73], v[72:73], v[84:85]
	v_pk_add_f32 v[74:75], v[74:75], v[86:87]
	s_waitcnt lgkmcnt(0)
	v_pk_fma_f32 v[34:35], v[72:73], v[90:91], v[34:35]
	v_pk_fma_f32 v[32:33], v[74:75], v[88:89], v[32:33]
	global_store_dwordx4 v[166:167], v[36:39], off offset:2048
	global_store_dwordx4 v[166:167], v[32:35], off offset:3072
	s_branch .LBB0_902
